# attention loop: first QK MFMA one slot later (two PV MFMAs ahead of it) so its K fragments, read just behind the barrier, have landed
# speedup vs baseline: 1.0166x; 1.0100x over previous
; template <int KS> __device__ __forceinline__ void pv_ks(f32x16* o, int vb, bf16x8 pa) {
;     const s16x4 l0 = tr_read<v_rd_off(0, KS, 0)>(vb), h0 = tr_read<v_rd_off(0, KS, 1)>(vb), l1 = tr_read<v_rd_off(1, KS, 0)>(vb), h1 = tr_read<v_rd_off(1, KS, 1)>(vb);
;     const s16x4 l2 = tr_read<v_rd_off(2, KS, 0)>(vb), h2 = tr_read<v_rd_off(2, KS, 1)>(vb), l3 = tr_read<v_rd_off(3, KS, 0)>(vb), h3 = tr_read<v_rd_off(3, KS, 1)>(vb);
;     ...
;     asm volatile("s_waitcnt lgkmcnt(6)" ::: "memory"); SBAR();
;     o[0] = __builtin_amdgcn_mfma_f32_32x32x16_bf16(pa, PK(l0, h0), o[0], 0, 0, 0);
;     asm volatile("s_waitcnt lgkmcnt(4)" ::: "memory"); SBAR();
;     o[1] = __builtin_amdgcn_mfma_f32_32x32x16_bf16(pa, PK(l1, h1), o[1], 0, 0, 0);
;     asm volatile("s_waitcnt lgkmcnt(2)" ::: "memory"); SBAR();
;     o[2] = __builtin_amdgcn_mfma_f32_32x32x16_bf16(pa, PK(l2, h2), o[2], 0, 0, 0);
;     asm volatile("s_waitcnt lgkmcnt(0)" ::: "memory"); SBAR();
;     o[3] = __builtin_amdgcn_mfma_f32_32x32x16_bf16(pa, PK(l3, h3), o[3], 0, 0, 0);
;     ...
; }
; __device__ __forceinline__ void pv_d0(f32x16* o, int vb, bf16x8 pa0, bf16x8 pa1, bf16x8 pa2, bf16x8 pa3) {
;     __builtin_amdgcn_s_setprio(1);
;     pv_ks<0>(o, vb, pa0); pv_ks<1>(o, vb, pa1); pv_ks<2>(o, vb, pa2); pv_ks<3>(o, vb, pa3);
;     __builtin_amdgcn_s_setprio(0);
; }
; __device__ __forceinline__ void exp_half(f32x16& p) {
; #pragma unroll
;     for (int r = 0; r < 16; ++r) p[r] = __builtin_amdgcn_exp2f(p[r]);
; }
; __device__ __forceinline__ void pack_p(const f32x16& p0, const f32x16& p1, float& l_reg, bf16x8& pa0, bf16x8& pa1, bf16x8& pa2, bf16x8& pa3) {
;     float ps = 0;
; #pragma unroll
;     for (int r = 0; r < 16; ++r) ps += p0[r];
; #pragma unroll
;     for (int r = 0; r < 16; ++r) ps += p1[r];
;     l_reg += ps;
;     ...
;     PK4(p0, 0, pa0); PK4(p0, 8, pa1); PK4(p1, 0, pa2); PK4(p1, 8, pa3);
;     ...
; }
; template <int ND0> __device__ __forceinline__ void qkt(f32x16& p0, f32x16& p1, const char* Ks, const bf16x8* qr, int r32, int hi, int colB0) {
; #pragma unroll
;     for (int d0 = 0; d0 < ND0; ++d0) { const int cb = colB0 + (d0 * 16 + hi * 8) * 2;
;         const bf16x8 b0 = *reinterpret_cast<const bf16x8*>(Ks + KSWZ(r32, cb));
;         const bf16x8 b1 = *reinterpret_cast<const bf16x8*>(Ks + KSWZ(32 + r32, cb));
;         p0 = __builtin_amdgcn_mfma_f32_32x32x16_bf16(b0, qr[d0], p0, 0, 0, 0);
.Lsym_nostage_s0:
	s_waitcnt lgkmcnt(14)
	v_mfma_f32_32x32x16_bf16 v[48:63], v[128:131], v[144:147], v[48:63]
	ds_read_b64_tr_b16 v[144:145], v252 offset:4096
	ds_read_b64_tr_b16 v[146:147], v252 offset:6144
	v_exp_f32_e32 v88, v88
	v_exp_f32_e32 v89, v89
	v_exp_f32_e32 v90, v90
	s_waitcnt lgkmcnt(14)
	v_mfma_f32_32x32x16_bf16 v[32:47], v[128:131], v[148:151], v[32:47]
	ds_read_b64_tr_b16 v[148:149], v252 offset:4608
	ds_read_b64_tr_b16 v[150:151], v252 offset:6656
	v_exp_f32_e32 v91, v91
	v_add_f32_e32 v182, v88, v182
	v_add_f32_e32 v182, v89, v182
	v_cvt_pk_bf16_f32 v132, v88, v89
	v_exp_f32_e32 v92, v92
	s_waitcnt lgkmcnt(11)
	v_mfma_f32_32x32x16_bf16 v[112:127], v[192:195], v[172:175], v[112:127]
	v_exp_f32_e32 v93, v93
	v_add_f32_e32 v182, v90, v182
	v_add_f32_e32 v182, v91, v182
	v_cvt_pk_bf16_f32 v133, v90, v91
	v_mfma_f32_32x32x16_bf16 v[16:31], v[128:131], v[152:155], v[16:31]
	ds_read_b64_tr_b16 v[152:153], v252 offset:5120
	ds_read_b64_tr_b16 v[154:155], v252 offset:7168
	v_exp_f32_e32 v94, v94
	v_exp_f32_e32 v95, v95
	v_add_f32_e32 v182, v92, v182
	v_add_f32_e32 v182, v93, v182
	s_waitcnt lgkmcnt(12)
	v_mfma_f32_32x32x16_bf16 v[96:111], v[196:199], v[172:175], v[96:111]
	v_cvt_pk_bf16_f32 v134, v92, v93
	v_cvt_pk_bf16_f32 v135, v94, v95
	v_add_f32_e32 v182, v94, v182
	v_add_f32_e32 v182, v95, v182
	v_exp_f32_e32 v64, v64
	v_mfma_f32_32x32x16_bf16 v[0:15], v[128:131], v[156:159], v[0:15]
	ds_read_b64_tr_b16 v[156:157], v252 offset:5632
	ds_read_b64_tr_b16 v[158:159], v252 offset:7680
	v_exp_f32_e32 v65, v65
	v_exp_f32_e32 v66, v66
	v_exp_f32_e32 v67, v67
	v_add_f32_e32 v182, v64, v182
	s_waitcnt lgkmcnt(13)
	v_mfma_f32_32x32x16_bf16 v[112:127], v[200:203], v[168:171], v[112:127]
	v_add_f32_e32 v182, v65, v182
	v_cvt_pk_bf16_f32 v136, v64, v65
	v_exp_f32_e32 v68, v68
	v_exp_f32_e32 v69, v69
	s_waitcnt lgkmcnt(6)
	v_mfma_f32_32x32x16_bf16 v[48:63], v[132:135], v[144:147], v[48:63]
	ds_read_b64_tr_b16 v[144:145], v252 offset:8192
	ds_read_b64_tr_b16 v[146:147], v252 offset:10240
	v_add_f32_e32 v182, v66, v182
	v_add_f32_e32 v182, v67, v182
	v_cvt_pk_bf16_f32 v137, v66, v67
	v_exp_f32_e32 v70, v70
	v_mfma_f32_32x32x16_bf16 v[96:111], v[204:207], v[168:171], v[96:111]
	v_exp_f32_e32 v71, v71
	v_add_f32_e32 v182, v68, v182
	v_add_f32_e32 v182, v69, v182
	v_cvt_pk_bf16_f32 v138, v68, v69
	v_cvt_pk_bf16_f32 v139, v70, v71
	v_add_f32_e32 v182, v70, v182
	s_waitcnt lgkmcnt(6)
	v_mfma_f32_32x32x16_bf16 v[32:47], v[132:135], v[148:151], v[32:47]
	ds_read_b64_tr_b16 v[148:149], v252 offset:8704
	ds_read_b64_tr_b16 v[150:151], v252 offset:10752
	v_add_f32_e32 v182, v71, v182
	v_exp_f32_e32 v72, v72
	v_exp_f32_e32 v73, v73
	v_exp_f32_e32 v74, v74
	v_mfma_f32_32x32x16_bf16 v[112:127], v[208:211], v[164:167], v[112:127]
	v_exp_f32_e32 v75, v75
	v_add_f32_e32 v182, v72, v182
	v_add_f32_e32 v182, v73, v182
	v_cvt_pk_bf16_f32 v140, v72, v73
	s_waitcnt lgkmcnt(6)
	v_mfma_f32_32x32x16_bf16 v[16:31], v[132:135], v[152:155], v[16:31]
	ds_read_b64_tr_b16 v[152:153], v252 offset:9216
	ds_read_b64_tr_b16 v[154:155], v252 offset:11264
	v_exp_f32_e32 v76, v76
	v_exp_f32_e32 v77, v77
	v_add_f32_e32 v182, v74, v182
	v_add_f32_e32 v182, v75, v182
	v_mfma_f32_32x32x16_bf16 v[96:111], v[212:215], v[164:167], v[96:111]
	v_cvt_pk_bf16_f32 v141, v74, v75
	v_exp_f32_e32 v78, v78
	v_exp_f32_e32 v79, v79
	v_add_f32_e32 v182, v76, v182
	s_waitcnt lgkmcnt(6)
	v_mfma_f32_32x32x16_bf16 v[0:15], v[132:135], v[156:159], v[0:15]
	ds_read_b64_tr_b16 v[156:157], v252 offset:9728
	ds_read_b64_tr_b16 v[158:159], v252 offset:11776
	v_add_f32_e32 v182, v77, v182
	v_cvt_pk_bf16_f32 v142, v76, v77
	v_cvt_pk_bf16_f32 v143, v78, v79
	v_add_f32_e32 v182, v78, v182
	v_add_f32_e32 v182, v79, v182
	s_cmp_lt_i32 s55, 0
	s_cselect_b32 s100, -1.0, 1.0
	v_mul_f32_e32 v185, s100, v186
	v_mfma_f32_32x32x16_bf16 v[112:127], v[216:219], v[160:163], v[112:127]
	v_fma_f32 v187, -v185, v183, s16
	v_fmamk_f32 v80, v185, 0x00000000, v187
	v_fmamk_f32 v81, v185, 0x3f800000, v187
	v_fmamk_f32 v82, v185, 0x40000000, v187
	v_fmamk_f32 v83, v185, 0x40400000, v187
	v_fmamk_f32 v84, v185, 0x41000000, v187
	v_mfma_f32_32x32x16_bf16 v[96:111], v[220:223], v[160:163], v[96:111]
	v_fmamk_f32 v85, v185, 0x41100000, v187
	v_fmamk_f32 v86, v185, 0x41200000, v187
	v_fmamk_f32 v87, v185, 0x41300000, v187
	v_fmamk_f32 v88, v185, 0x41800000, v187
	v_fmamk_f32 v89, v185, 0x41880000, v187
	v_fmamk_f32 v90, v185, 0x41900000, v187
	s_waitcnt lgkmcnt(6)
	v_mfma_f32_32x32x16_bf16 v[48:63], v[136:139], v[144:147], v[48:63]
	ds_read_b64_tr_b16 v[144:145], v252 offset:12288
	ds_read_b64_tr_b16 v[146:147], v252 offset:14336
	v_fmamk_f32 v91, v185, 0x41980000, v187
	v_fmamk_f32 v92, v185, 0x41c00000, v187
	v_fmamk_f32 v93, v185, 0x41c80000, v187
	v_fmamk_f32 v94, v185, 0x41d00000, v187
	v_fmamk_f32 v95, v185, 0x41d80000, v187
	v_fmamk_f32 v64, v185, 0x42000000, v187
	s_waitcnt lgkmcnt(6)
; #define SBAR() __builtin_amdgcn_sched_barrier(0)
; template <int KS> __device__ __forceinline__ void pv_ks(f32x16* o, int vb, bf16x8 pa) {
;     const s16x4 l0 = tr_read<v_rd_off(0, KS, 0)>(vb), h0 = tr_read<v_rd_off(0, KS, 1)>(vb), l1 = tr_read<v_rd_off(1, KS, 0)>(vb), h1 = tr_read<v_rd_off(1, KS, 1)>(vb);
;     const s16x4 l2 = tr_read<v_rd_off(2, KS, 0)>(vb), h2 = tr_read<v_rd_off(2, KS, 1)>(vb), l3 = tr_read<v_rd_off(3, KS, 0)>(vb), h3 = tr_read<v_rd_off(3, KS, 1)>(vb);
;     ...
;     asm volatile("s_waitcnt lgkmcnt(6)" ::: "memory"); SBAR();
;     o[0] = __builtin_amdgcn_mfma_f32_32x32x16_bf16(pa, PK(l0, h0), o[0], 0, 0, 0);
;     asm volatile("s_waitcnt lgkmcnt(4)" ::: "memory"); SBAR();
;     o[1] = __builtin_amdgcn_mfma_f32_32x32x16_bf16(pa, PK(l1, h1), o[1], 0, 0, 0);
;     asm volatile("s_waitcnt lgkmcnt(2)" ::: "memory"); SBAR();
;     o[2] = __builtin_amdgcn_mfma_f32_32x32x16_bf16(pa, PK(l2, h2), o[2], 0, 0, 0);
;     asm volatile("s_waitcnt lgkmcnt(0)" ::: "memory"); SBAR();
;     o[3] = __builtin_amdgcn_mfma_f32_32x32x16_bf16(pa, PK(l3, h3), o[3], 0, 0, 0);
;     ...
; }
; __device__ __forceinline__ void pv_d0(f32x16* o, int vb, bf16x8 pa0, bf16x8 pa1, bf16x8 pa2, bf16x8 pa3) {
;     __builtin_amdgcn_s_setprio(1);
;     pv_ks<0>(o, vb, pa0); pv_ks<1>(o, vb, pa1); pv_ks<2>(o, vb, pa2); pv_ks<3>(o, vb, pa3);
;     __builtin_amdgcn_s_setprio(0);
; }
; __device__ __forceinline__ void exp_half(f32x16& p) {
; #pragma unroll
;     for (int r = 0; r < 16; ++r) p[r] = __builtin_amdgcn_exp2f(p[r]);
; }
; __device__ __forceinline__ void pack_p(const f32x16& p0, const f32x16& p1, float& l_reg, bf16x8& pa0, bf16x8& pa1, bf16x8& pa2, bf16x8& pa3) {
;     float ps = 0;
; #pragma unroll
;     for (int r = 0; r < 16; ++r) ps += p0[r];
; #pragma unroll
;     for (int r = 0; r < 16; ++r) ps += p1[r];
;     l_reg += ps;
;     ...
;     PK4(p0, 0, pa0); PK4(p0, 8, pa1); PK4(p1, 0, pa2); PK4(p1, 8, pa3);
;     ...
; }
; __device__ __forceinline__ void bias_init(f32x16& p0, f32x16& p1, float base, float nslope2, float nM2, int rel  ) {
;     if (rel <= -63 || rel >= 31) {
;         const float sg = (rel < 0) ? -nslope2 : nslope2, lbv = fmaf(-sg, base, nM2);
; #pragma unroll
;         for (int r = 0; r < 16; ++r) { p0[r] = fmaf((float)((r & 3) + 8 * (r >> 2)), sg, lbv); p1[r] = fmaf((float)((r & 3) + 8 * (r >> 2) + 32), sg, lbv); }
;     } else {
; #pragma unroll
	v_mfma_f32_32x32x16_bf16 v[32:47], v[136:139], v[148:151], v[32:47]
	ds_read_b64_tr_b16 v[148:149], v252 offset:12800
	ds_read_b64_tr_b16 v[150:151], v252 offset:14848
	v_fmamk_f32 v65, v185, 0x42040000, v187
	v_fmamk_f32 v66, v185, 0x42080000, v187
	v_fmamk_f32 v67, v185, 0x420c0000, v187
	v_fmamk_f32 v68, v185, 0x42200000, v187
	v_fmamk_f32 v69, v185, 0x42240000, v187
	v_fmamk_f32 v70, v185, 0x42280000, v187
	s_waitcnt lgkmcnt(6)
	v_mfma_f32_32x32x16_bf16 v[16:31], v[136:139], v[152:155], v[16:31]
	ds_read_b64_tr_b16 v[152:153], v252 offset:13312
	ds_read_b64_tr_b16 v[154:155], v252 offset:15360
	v_fmamk_f32 v71, v185, 0x422c0000, v187
	v_fmamk_f32 v72, v185, 0x42400000, v187
	v_fmamk_f32 v73, v185, 0x42440000, v187
	v_fmamk_f32 v74, v185, 0x42480000, v187
	v_fmamk_f32 v75, v185, 0x424c0000, v187
	v_fmamk_f32 v76, v185, 0x42600000, v187
	s_waitcnt lgkmcnt(6)
	v_mfma_f32_32x32x16_bf16 v[0:15], v[136:139], v[156:159], v[0:15]
	ds_read_b64_tr_b16 v[156:157], v252 offset:13824
	ds_read_b64_tr_b16 v[158:159], v252 offset:15872
	v_fmamk_f32 v77, v185, 0x42640000, v187
	v_fmamk_f32 v78, v185, 0x42680000, v187
	v_fmamk_f32 v79, v185, 0x426c0000, v187
	v_exp_f32_e32 v112, v112
	v_exp_f32_e32 v113, v113
	s_waitcnt lgkmcnt(6)
	v_mfma_f32_32x32x16_bf16 v[48:63], v[140:143], v[144:147], v[48:63]
	ds_read_b64_tr_b16 v[144:145], v252 offset:16384
	ds_read_b64_tr_b16 v[146:147], v252 offset:18432
	v_exp_f32_e32 v114, v114
	v_exp_f32_e32 v115, v115
	v_add_f32_e32 v182, v112, v182
	v_add_f32_e32 v182, v113, v182
	s_waitcnt lgkmcnt(6)
	v_mfma_f32_32x32x16_bf16 v[32:47], v[140:143], v[148:151], v[32:47]
	ds_read_b64_tr_b16 v[148:149], v252 offset:16896
	ds_read_b64_tr_b16 v[150:151], v252 offset:18944
	v_cvt_pk_bf16_f32 v128, v112, v113
	v_exp_f32_e32 v116, v116
	v_exp_f32_e32 v117, v117
	v_add_f32_e32 v182, v114, v182
	s_waitcnt lgkmcnt(6)
	v_mfma_f32_32x32x16_bf16 v[16:31], v[140:143], v[152:155], v[16:31]
	ds_read_b64_tr_b16 v[152:153], v252 offset:17408
	ds_read_b64_tr_b16 v[154:155], v252 offset:19456
	v_add_f32_e32 v182, v115, v182
	v_cvt_pk_bf16_f32 v129, v114, v115
	v_exp_f32_e32 v118, v118
	v_exp_f32_e32 v119, v119
	s_waitcnt lgkmcnt(6)
	v_mfma_f32_32x32x16_bf16 v[0:15], v[140:143], v[156:159], v[0:15]
	ds_read_b64_tr_b16 v[156:157], v252 offset:17920
	ds_read_b64_tr_b16 v[158:159], v252 offset:19968
	v_add_f32_e32 v182, v116, v182
	v_add_f32_e32 v182, v117, v182
	v_cvt_pk_bf16_f32 v130, v116, v117
	v_cvt_pk_bf16_f32 v131, v118, v119
	v_add_f32_e32 v182, v118, v182
	v_add_f32_e32 v182, v119, v182
	s_add_i32 s100, s55, 62
	s_cmp_lt_u32 s100, 93
	s_cbranch_scc0 .Lsym_nodiag_s0
	v_add_f32_e32 v190, 0x00000000, v183
	v_add_f32_e32 v191, 0xc2000000, v183
	v_fma_f32 v80, |v190|, v186, s16
	v_fma_f32 v64, |v191|, v186, s16
	v_add_f32_e32 v190, 0xbf800000, v183
	v_add_f32_e32 v191, 0xc2040000, v183
	v_fma_f32 v81, |v190|, v186, s16
	v_fma_f32 v65, |v191|, v186, s16
	v_add_f32_e32 v190, 0xc0000000, v183
	v_add_f32_e32 v191, 0xc2080000, v183
	v_fma_f32 v82, |v190|, v186, s16
	v_fma_f32 v66, |v191|, v186, s16
	v_add_f32_e32 v190, 0xc0400000, v183
	v_add_f32_e32 v191, 0xc20c0000, v183
	v_fma_f32 v83, |v190|, v186, s16
	v_fma_f32 v67, |v191|, v186, s16
	v_add_f32_e32 v190, 0xc1000000, v183
	v_add_f32_e32 v191, 0xc2200000, v183
	v_fma_f32 v84, |v190|, v186, s16
	v_fma_f32 v68, |v191|, v186, s16
	v_add_f32_e32 v190, 0xc1100000, v183
	v_add_f32_e32 v191, 0xc2240000, v183
	v_fma_f32 v85, |v190|, v186, s16
	v_fma_f32 v69, |v191|, v186, s16
	v_add_f32_e32 v190, 0xc1200000, v183
	v_add_f32_e32 v191, 0xc2280000, v183
	v_fma_f32 v86, |v190|, v186, s16
	v_fma_f32 v70, |v191|, v186, s16
	v_add_f32_e32 v190, 0xc1300000, v183
	v_add_f32_e32 v191, 0xc22c0000, v183
	v_fma_f32 v87, |v190|, v186, s16
	v_fma_f32 v71, |v191|, v186, s16
	v_add_f32_e32 v190, 0xc1800000, v183
	v_add_f32_e32 v191, 0xc2400000, v183
	v_fma_f32 v88, |v190|, v186, s16
	v_fma_f32 v72, |v191|, v186, s16
	v_add_f32_e32 v190, 0xc1880000, v183
	v_add_f32_e32 v191, 0xc2440000, v183
	v_fma_f32 v89, |v190|, v186, s16
	v_fma_f32 v73, |v191|, v186, s16
	v_add_f32_e32 v190, 0xc1900000, v183
	v_add_f32_e32 v191, 0xc2480000, v183
	v_fma_f32 v90, |v190|, v186, s16
	v_fma_f32 v74, |v191|, v186, s16
	v_add_f32_e32 v190, 0xc1980000, v183
	v_add_f32_e32 v191, 0xc24c0000, v183
	v_fma_f32 v91, |v190|, v186, s16
	v_fma_f32 v75, |v191|, v186, s16
	v_add_f32_e32 v190, 0xc1c00000, v183
	v_add_f32_e32 v191, 0xc2600000, v183
	v_fma_f32 v92, |v190|, v186, s16
	v_fma_f32 v76, |v191|, v186, s16
	v_add_f32_e32 v190, 0xc1c80000, v183
	v_add_f32_e32 v191, 0xc2640000, v183
	v_fma_f32 v93, |v190|, v186, s16
	v_fma_f32 v77, |v191|, v186, s16
	v_add_f32_e32 v190, 0xc1d00000, v183
	v_add_f32_e32 v191, 0xc2680000, v183
	v_fma_f32 v94, |v190|, v186, s16
	v_fma_f32 v78, |v191|, v186, s16
	v_add_f32_e32 v190, 0xc1d80000, v183
	v_add_f32_e32 v191, 0xc26c0000, v183
	v_fma_f32 v95, |v190|, v186, s16
	v_fma_f32 v79, |v191|, v186, s16

; template <int KS> __device__ __forceinline__ void pv_ks(f32x16* o, int vb, bf16x8 pa) {
;     const s16x4 l0 = tr_read<v_rd_off(0, KS, 0)>(vb), h0 = tr_read<v_rd_off(0, KS, 1)>(vb), l1 = tr_read<v_rd_off(1, KS, 0)>(vb), h1 = tr_read<v_rd_off(1, KS, 1)>(vb);
;     const s16x4 l2 = tr_read<v_rd_off(2, KS, 0)>(vb), h2 = tr_read<v_rd_off(2, KS, 1)>(vb), l3 = tr_read<v_rd_off(3, KS, 0)>(vb), h3 = tr_read<v_rd_off(3, KS, 1)>(vb);
;     ...
;     asm volatile("s_waitcnt lgkmcnt(6)" ::: "memory"); SBAR();
;     o[0] = __builtin_amdgcn_mfma_f32_32x32x16_bf16(pa, PK(l0, h0), o[0], 0, 0, 0);
;     asm volatile("s_waitcnt lgkmcnt(4)" ::: "memory"); SBAR();
;     o[1] = __builtin_amdgcn_mfma_f32_32x32x16_bf16(pa, PK(l1, h1), o[1], 0, 0, 0);
;     asm volatile("s_waitcnt lgkmcnt(2)" ::: "memory"); SBAR();
;     o[2] = __builtin_amdgcn_mfma_f32_32x32x16_bf16(pa, PK(l2, h2), o[2], 0, 0, 0);
;     asm volatile("s_waitcnt lgkmcnt(0)" ::: "memory"); SBAR();
;     o[3] = __builtin_amdgcn_mfma_f32_32x32x16_bf16(pa, PK(l3, h3), o[3], 0, 0, 0);
;     ...
; }
; __device__ __forceinline__ void pv_d0(f32x16* o, int vb, bf16x8 pa0, bf16x8 pa1, bf16x8 pa2, bf16x8 pa3) {
;     __builtin_amdgcn_s_setprio(1);
;     pv_ks<0>(o, vb, pa0); pv_ks<1>(o, vb, pa1); pv_ks<2>(o, vb, pa2); pv_ks<3>(o, vb, pa3);
;     __builtin_amdgcn_s_setprio(0);
; }
; __device__ __forceinline__ void exp_half(f32x16& p) {
; #pragma unroll
;     for (int r = 0; r < 16; ++r) p[r] = __builtin_amdgcn_exp2f(p[r]);
; }
; __device__ __forceinline__ void pack_p(const f32x16& p0, const f32x16& p1, float& l_reg, bf16x8& pa0, bf16x8& pa1, bf16x8& pa2, bf16x8& pa3) {
;     float ps = 0;
; #pragma unroll
;     for (int r = 0; r < 16; ++r) ps += p0[r];
; #pragma unroll
;     for (int r = 0; r < 16; ++r) ps += p1[r];
;     l_reg += ps;
;     ...
;     PK4(p0, 0, pa0); PK4(p0, 8, pa1); PK4(p1, 0, pa2); PK4(p1, 8, pa3);
;     ...
; }
; template <int ND0> __device__ __forceinline__ void qkt(f32x16& p0, f32x16& p1, const char* Ks, const bf16x8* qr, int r32, int hi, int colB0) {
; #pragma unroll
;     for (int d0 = 0; d0 < ND0; ++d0) { const int cb = colB0 + (d0 * 16 + hi * 8) * 2;
;         const bf16x8 b0 = *reinterpret_cast<const bf16x8*>(Ks + KSWZ(r32, cb));
;         const bf16x8 b1 = *reinterpret_cast<const bf16x8*>(Ks + KSWZ(32 + r32, cb));
;         p0 = __builtin_amdgcn_mfma_f32_32x32x16_bf16(b0, qr[d0], p0, 0, 0, 0);
.Lsym_nostage_s1:
	s_waitcnt lgkmcnt(14)
	v_mfma_f32_32x32x16_bf16 v[48:63], v[128:131], v[144:147], v[48:63]
	ds_read_b64_tr_b16 v[144:145], v252 offset:20480
	ds_read_b64_tr_b16 v[146:147], v252 offset:22528
	v_exp_f32_e32 v120, v120
	v_exp_f32_e32 v121, v121
	v_exp_f32_e32 v122, v122
	s_waitcnt lgkmcnt(14)
	v_mfma_f32_32x32x16_bf16 v[32:47], v[128:131], v[148:151], v[32:47]
	ds_read_b64_tr_b16 v[148:149], v252 offset:20992
	ds_read_b64_tr_b16 v[150:151], v252 offset:23040
	v_exp_f32_e32 v123, v123
	v_add_f32_e32 v182, v120, v182
	v_add_f32_e32 v182, v121, v182
	v_cvt_pk_bf16_f32 v132, v120, v121
	v_exp_f32_e32 v124, v124
	s_waitcnt lgkmcnt(11)
	v_mfma_f32_32x32x16_bf16 v[80:95], v[192:195], v[172:175], v[80:95]
	v_exp_f32_e32 v125, v125
	v_add_f32_e32 v182, v122, v182
	v_add_f32_e32 v182, v123, v182
	v_cvt_pk_bf16_f32 v133, v122, v123
	v_mfma_f32_32x32x16_bf16 v[16:31], v[128:131], v[152:155], v[16:31]
	ds_read_b64_tr_b16 v[152:153], v252 offset:21504
	ds_read_b64_tr_b16 v[154:155], v252 offset:23552
	v_exp_f32_e32 v126, v126
	v_exp_f32_e32 v127, v127
	v_add_f32_e32 v182, v124, v182
	v_add_f32_e32 v182, v125, v182
	s_waitcnt lgkmcnt(12)
	v_mfma_f32_32x32x16_bf16 v[64:79], v[196:199], v[172:175], v[64:79]
	v_cvt_pk_bf16_f32 v134, v124, v125
	v_cvt_pk_bf16_f32 v135, v126, v127
	v_add_f32_e32 v182, v126, v182
	v_add_f32_e32 v182, v127, v182
	v_exp_f32_e32 v96, v96
	v_mfma_f32_32x32x16_bf16 v[0:15], v[128:131], v[156:159], v[0:15]
	ds_read_b64_tr_b16 v[156:157], v252 offset:22016
	ds_read_b64_tr_b16 v[158:159], v252 offset:24064
	v_exp_f32_e32 v97, v97
	v_exp_f32_e32 v98, v98
	v_exp_f32_e32 v99, v99
	v_add_f32_e32 v182, v96, v182
	s_waitcnt lgkmcnt(13)
	v_mfma_f32_32x32x16_bf16 v[80:95], v[200:203], v[168:171], v[80:95]
	v_add_f32_e32 v182, v97, v182
	v_cvt_pk_bf16_f32 v136, v96, v97
	v_exp_f32_e32 v100, v100
	v_exp_f32_e32 v101, v101
	s_waitcnt lgkmcnt(6)
	v_mfma_f32_32x32x16_bf16 v[48:63], v[132:135], v[144:147], v[48:63]
	ds_read_b64_tr_b16 v[144:145], v252 offset:24576
	ds_read_b64_tr_b16 v[146:147], v252 offset:26624
	v_add_f32_e32 v182, v98, v182
	v_add_f32_e32 v182, v99, v182
	v_cvt_pk_bf16_f32 v137, v98, v99
	v_exp_f32_e32 v102, v102
	v_mfma_f32_32x32x16_bf16 v[64:79], v[204:207], v[168:171], v[64:79]
	v_exp_f32_e32 v103, v103
	v_add_f32_e32 v182, v100, v182
	v_add_f32_e32 v182, v101, v182
	v_cvt_pk_bf16_f32 v138, v100, v101
	v_cvt_pk_bf16_f32 v139, v102, v103
	v_add_f32_e32 v182, v102, v182
	s_waitcnt lgkmcnt(6)
	v_mfma_f32_32x32x16_bf16 v[32:47], v[132:135], v[148:151], v[32:47]
	ds_read_b64_tr_b16 v[148:149], v252 offset:25088
	ds_read_b64_tr_b16 v[150:151], v252 offset:27136
	v_add_f32_e32 v182, v103, v182
	v_exp_f32_e32 v104, v104
	v_exp_f32_e32 v105, v105
	v_exp_f32_e32 v106, v106
	v_mfma_f32_32x32x16_bf16 v[80:95], v[208:211], v[164:167], v[80:95]
	v_exp_f32_e32 v107, v107
	v_add_f32_e32 v182, v104, v182
	v_add_f32_e32 v182, v105, v182
	v_cvt_pk_bf16_f32 v140, v104, v105
	s_waitcnt lgkmcnt(6)
	v_mfma_f32_32x32x16_bf16 v[16:31], v[132:135], v[152:155], v[16:31]
	ds_read_b64_tr_b16 v[152:153], v252 offset:25600
	ds_read_b64_tr_b16 v[154:155], v252 offset:27648
	v_exp_f32_e32 v108, v108
	v_exp_f32_e32 v109, v109
	v_add_f32_e32 v182, v106, v182
	v_add_f32_e32 v182, v107, v182
	v_mfma_f32_32x32x16_bf16 v[64:79], v[212:215], v[164:167], v[64:79]
	v_cvt_pk_bf16_f32 v141, v106, v107
	v_exp_f32_e32 v110, v110
	v_exp_f32_e32 v111, v111
	v_add_f32_e32 v182, v108, v182
	s_waitcnt lgkmcnt(6)
	v_mfma_f32_32x32x16_bf16 v[0:15], v[132:135], v[156:159], v[0:15]
	ds_read_b64_tr_b16 v[156:157], v252 offset:26112
	ds_read_b64_tr_b16 v[158:159], v252 offset:28160
	v_add_f32_e32 v182, v109, v182
	v_cvt_pk_bf16_f32 v142, v108, v109
	v_cvt_pk_bf16_f32 v143, v110, v111
	v_add_f32_e32 v182, v110, v182
	v_add_f32_e32 v182, v111, v182
	s_cmp_lt_i32 s55, 0
	s_cselect_b32 s100, -1.0, 1.0
	v_mul_f32_e32 v185, s100, v186
	v_mfma_f32_32x32x16_bf16 v[80:95], v[216:219], v[160:163], v[80:95]
	v_fma_f32 v187, -v185, v183, s16
	v_fmamk_f32 v112, v185, 0x00000000, v187
	v_fmamk_f32 v113, v185, 0x3f800000, v187
	v_fmamk_f32 v114, v185, 0x40000000, v187
	v_fmamk_f32 v115, v185, 0x40400000, v187
	v_fmamk_f32 v116, v185, 0x41000000, v187
	v_mfma_f32_32x32x16_bf16 v[64:79], v[220:223], v[160:163], v[64:79]
	v_fmamk_f32 v117, v185, 0x41100000, v187
	v_fmamk_f32 v118, v185, 0x41200000, v187
	v_fmamk_f32 v119, v185, 0x41300000, v187
	v_fmamk_f32 v120, v185, 0x41800000, v187
	v_fmamk_f32 v121, v185, 0x41880000, v187
	v_fmamk_f32 v122, v185, 0x41900000, v187
	s_waitcnt lgkmcnt(6)
	v_mfma_f32_32x32x16_bf16 v[48:63], v[136:139], v[144:147], v[48:63]
	ds_read_b64_tr_b16 v[144:145], v252 offset:28672
	ds_read_b64_tr_b16 v[146:147], v252 offset:30720
	v_fmamk_f32 v123, v185, 0x41980000, v187
	v_fmamk_f32 v124, v185, 0x41c00000, v187
	v_fmamk_f32 v125, v185, 0x41c80000, v187
	v_fmamk_f32 v126, v185, 0x41d00000, v187
	v_fmamk_f32 v127, v185, 0x41d80000, v187
	v_fmamk_f32 v96, v185, 0x42000000, v187
	s_waitcnt lgkmcnt(6)
; #define SBAR() __builtin_amdgcn_sched_barrier(0)
; template <int KS> __device__ __forceinline__ void pv_ks(f32x16* o, int vb, bf16x8 pa) {
;     const s16x4 l0 = tr_read<v_rd_off(0, KS, 0)>(vb), h0 = tr_read<v_rd_off(0, KS, 1)>(vb), l1 = tr_read<v_rd_off(1, KS, 0)>(vb), h1 = tr_read<v_rd_off(1, KS, 1)>(vb);
;     const s16x4 l2 = tr_read<v_rd_off(2, KS, 0)>(vb), h2 = tr_read<v_rd_off(2, KS, 1)>(vb), l3 = tr_read<v_rd_off(3, KS, 0)>(vb), h3 = tr_read<v_rd_off(3, KS, 1)>(vb);
;     ...
;     asm volatile("s_waitcnt lgkmcnt(6)" ::: "memory"); SBAR();
;     o[0] = __builtin_amdgcn_mfma_f32_32x32x16_bf16(pa, PK(l0, h0), o[0], 0, 0, 0);
;     asm volatile("s_waitcnt lgkmcnt(4)" ::: "memory"); SBAR();
;     o[1] = __builtin_amdgcn_mfma_f32_32x32x16_bf16(pa, PK(l1, h1), o[1], 0, 0, 0);
;     asm volatile("s_waitcnt lgkmcnt(2)" ::: "memory"); SBAR();
;     o[2] = __builtin_amdgcn_mfma_f32_32x32x16_bf16(pa, PK(l2, h2), o[2], 0, 0, 0);
;     asm volatile("s_waitcnt lgkmcnt(0)" ::: "memory"); SBAR();
;     o[3] = __builtin_amdgcn_mfma_f32_32x32x16_bf16(pa, PK(l3, h3), o[3], 0, 0, 0);
;     ...
; }
; __device__ __forceinline__ void pv_d0(f32x16* o, int vb, bf16x8 pa0, bf16x8 pa1, bf16x8 pa2, bf16x8 pa3) {
;     __builtin_amdgcn_s_setprio(1);
;     pv_ks<0>(o, vb, pa0); pv_ks<1>(o, vb, pa1); pv_ks<2>(o, vb, pa2); pv_ks<3>(o, vb, pa3);
;     __builtin_amdgcn_s_setprio(0);
; }
; __device__ __forceinline__ void exp_half(f32x16& p) {
; #pragma unroll
;     for (int r = 0; r < 16; ++r) p[r] = __builtin_amdgcn_exp2f(p[r]);
; }
; __device__ __forceinline__ void pack_p(const f32x16& p0, const f32x16& p1, float& l_reg, bf16x8& pa0, bf16x8& pa1, bf16x8& pa2, bf16x8& pa3) {
;     float ps = 0;
; #pragma unroll
;     for (int r = 0; r < 16; ++r) ps += p0[r];
; #pragma unroll
;     for (int r = 0; r < 16; ++r) ps += p1[r];
;     l_reg += ps;
;     ...
;     PK4(p0, 0, pa0); PK4(p0, 8, pa1); PK4(p1, 0, pa2); PK4(p1, 8, pa3);
;     ...
; }
; __device__ __forceinline__ void bias_init(f32x16& p0, f32x16& p1, float base, float nslope2, float nM2, int rel  ) {
;     if (rel <= -63 || rel >= 31) {
;         const float sg = (rel < 0) ? -nslope2 : nslope2, lbv = fmaf(-sg, base, nM2);
; #pragma unroll
;         for (int r = 0; r < 16; ++r) { p0[r] = fmaf((float)((r & 3) + 8 * (r >> 2)), sg, lbv); p1[r] = fmaf((float)((r & 3) + 8 * (r >> 2) + 32), sg, lbv); }
;     } else {
; #pragma unroll
	v_mfma_f32_32x32x16_bf16 v[32:47], v[136:139], v[148:151], v[32:47]
	ds_read_b64_tr_b16 v[148:149], v252 offset:29184
	ds_read_b64_tr_b16 v[150:151], v252 offset:31232
	v_fmamk_f32 v97, v185, 0x42040000, v187
	v_fmamk_f32 v98, v185, 0x42080000, v187
	v_fmamk_f32 v99, v185, 0x420c0000, v187
	v_fmamk_f32 v100, v185, 0x42200000, v187
	v_fmamk_f32 v101, v185, 0x42240000, v187
	v_fmamk_f32 v102, v185, 0x42280000, v187
	s_waitcnt lgkmcnt(6)
	v_mfma_f32_32x32x16_bf16 v[16:31], v[136:139], v[152:155], v[16:31]
	ds_read_b64_tr_b16 v[152:153], v252 offset:29696
	ds_read_b64_tr_b16 v[154:155], v252 offset:31744
	v_fmamk_f32 v103, v185, 0x422c0000, v187
	v_fmamk_f32 v104, v185, 0x42400000, v187
	v_fmamk_f32 v105, v185, 0x42440000, v187
	v_fmamk_f32 v106, v185, 0x42480000, v187
	v_fmamk_f32 v107, v185, 0x424c0000, v187
	v_fmamk_f32 v108, v185, 0x42600000, v187
	s_waitcnt lgkmcnt(6)
	v_mfma_f32_32x32x16_bf16 v[0:15], v[136:139], v[156:159], v[0:15]
	ds_read_b64_tr_b16 v[156:157], v252 offset:30208
	ds_read_b64_tr_b16 v[158:159], v252 offset:32256
	v_fmamk_f32 v109, v185, 0x42640000, v187
	v_fmamk_f32 v110, v185, 0x42680000, v187
	v_fmamk_f32 v111, v185, 0x426c0000, v187
	v_exp_f32_e32 v80, v80
	v_exp_f32_e32 v81, v81
	s_waitcnt lgkmcnt(6)
	v_mfma_f32_32x32x16_bf16 v[48:63], v[140:143], v[144:147], v[48:63]
	ds_read_b64_tr_b16 v[144:145], v252 offset:32768
	ds_read_b64_tr_b16 v[146:147], v252 offset:34816
	v_exp_f32_e32 v82, v82
	v_exp_f32_e32 v83, v83
	v_add_f32_e32 v182, v80, v182
	v_add_f32_e32 v182, v81, v182
	s_waitcnt lgkmcnt(6)
	v_mfma_f32_32x32x16_bf16 v[32:47], v[140:143], v[148:151], v[32:47]
	ds_read_b64_tr_b16 v[148:149], v252 offset:33280
	ds_read_b64_tr_b16 v[150:151], v252 offset:35328
	v_cvt_pk_bf16_f32 v128, v80, v81
	v_exp_f32_e32 v84, v84
	v_exp_f32_e32 v85, v85
	v_add_f32_e32 v182, v82, v182
	s_waitcnt lgkmcnt(6)
	v_mfma_f32_32x32x16_bf16 v[16:31], v[140:143], v[152:155], v[16:31]
	ds_read_b64_tr_b16 v[152:153], v252 offset:33792
	ds_read_b64_tr_b16 v[154:155], v252 offset:35840
	v_add_f32_e32 v182, v83, v182
	v_cvt_pk_bf16_f32 v129, v82, v83
	v_exp_f32_e32 v86, v86
	v_exp_f32_e32 v87, v87
	s_waitcnt lgkmcnt(6)
	v_mfma_f32_32x32x16_bf16 v[0:15], v[140:143], v[156:159], v[0:15]
	ds_read_b64_tr_b16 v[156:157], v252 offset:34304
	ds_read_b64_tr_b16 v[158:159], v252 offset:36352
	v_add_f32_e32 v182, v84, v182
	v_add_f32_e32 v182, v85, v182
	v_cvt_pk_bf16_f32 v130, v84, v85
	v_cvt_pk_bf16_f32 v131, v86, v87
	v_add_f32_e32 v182, v86, v182
	v_add_f32_e32 v182, v87, v182
	s_add_i32 s100, s55, 62
	s_cmp_lt_u32 s100, 93
	s_cbranch_scc0 .Lsym_nodiag_s1
	v_add_f32_e32 v190, 0x00000000, v183
	v_add_f32_e32 v191, 0xc2000000, v183
	v_fma_f32 v112, |v190|, v186, s16
	v_fma_f32 v96, |v191|, v186, s16
	v_add_f32_e32 v190, 0xbf800000, v183
	v_add_f32_e32 v191, 0xc2040000, v183
	v_fma_f32 v113, |v190|, v186, s16
	v_fma_f32 v97, |v191|, v186, s16
	v_add_f32_e32 v190, 0xc0000000, v183
	v_add_f32_e32 v191, 0xc2080000, v183
	v_fma_f32 v114, |v190|, v186, s16
	v_fma_f32 v98, |v191|, v186, s16
	v_add_f32_e32 v190, 0xc0400000, v183
	v_add_f32_e32 v191, 0xc20c0000, v183
	v_fma_f32 v115, |v190|, v186, s16
	v_fma_f32 v99, |v191|, v186, s16
	v_add_f32_e32 v190, 0xc1000000, v183
	v_add_f32_e32 v191, 0xc2200000, v183
	v_fma_f32 v116, |v190|, v186, s16
	v_fma_f32 v100, |v191|, v186, s16
	v_add_f32_e32 v190, 0xc1100000, v183
	v_add_f32_e32 v191, 0xc2240000, v183
	v_fma_f32 v117, |v190|, v186, s16
	v_fma_f32 v101, |v191|, v186, s16
	v_add_f32_e32 v190, 0xc1200000, v183
	v_add_f32_e32 v191, 0xc2280000, v183
	v_fma_f32 v118, |v190|, v186, s16
	v_fma_f32 v102, |v191|, v186, s16
	v_add_f32_e32 v190, 0xc1300000, v183
	v_add_f32_e32 v191, 0xc22c0000, v183
	v_fma_f32 v119, |v190|, v186, s16
	v_fma_f32 v103, |v191|, v186, s16
	v_add_f32_e32 v190, 0xc1800000, v183
	v_add_f32_e32 v191, 0xc2400000, v183
	v_fma_f32 v120, |v190|, v186, s16
	v_fma_f32 v104, |v191|, v186, s16
	v_add_f32_e32 v190, 0xc1880000, v183
	v_add_f32_e32 v191, 0xc2440000, v183
	v_fma_f32 v121, |v190|, v186, s16
	v_fma_f32 v105, |v191|, v186, s16
	v_add_f32_e32 v190, 0xc1900000, v183
	v_add_f32_e32 v191, 0xc2480000, v183
	v_fma_f32 v122, |v190|, v186, s16
	v_fma_f32 v106, |v191|, v186, s16
	v_add_f32_e32 v190, 0xc1980000, v183
	v_add_f32_e32 v191, 0xc24c0000, v183
	v_fma_f32 v123, |v190|, v186, s16
	v_fma_f32 v107, |v191|, v186, s16
	v_add_f32_e32 v190, 0xc1c00000, v183
	v_add_f32_e32 v191, 0xc2600000, v183
	v_fma_f32 v124, |v190|, v186, s16
	v_fma_f32 v108, |v191|, v186, s16
	v_add_f32_e32 v190, 0xc1c80000, v183
	v_add_f32_e32 v191, 0xc2640000, v183
	v_fma_f32 v125, |v190|, v186, s16
	v_fma_f32 v109, |v191|, v186, s16
	v_add_f32_e32 v190, 0xc1d00000, v183
	v_add_f32_e32 v191, 0xc2680000, v183
	v_fma_f32 v126, |v190|, v186, s16
	v_fma_f32 v110, |v191|, v186, s16
	v_add_f32_e32 v190, 0xc1d80000, v183
	v_add_f32_e32 v191, 0xc26c0000, v183
	v_fma_f32 v127, |v190|, v186, s16
	v_fma_f32 v111, |v191|, v186, s16

; template <int KS> __device__ __forceinline__ void pv_ks(f32x16* o, int vb, bf16x8 pa) {
;     const s16x4 l0 = tr_read<v_rd_off(0, KS, 0)>(vb), h0 = tr_read<v_rd_off(0, KS, 1)>(vb), l1 = tr_read<v_rd_off(1, KS, 0)>(vb), h1 = tr_read<v_rd_off(1, KS, 1)>(vb);
;     const s16x4 l2 = tr_read<v_rd_off(2, KS, 0)>(vb), h2 = tr_read<v_rd_off(2, KS, 1)>(vb), l3 = tr_read<v_rd_off(3, KS, 0)>(vb), h3 = tr_read<v_rd_off(3, KS, 1)>(vb);
;     ...
;     asm volatile("s_waitcnt lgkmcnt(6)" ::: "memory"); SBAR();
;     o[0] = __builtin_amdgcn_mfma_f32_32x32x16_bf16(pa, PK(l0, h0), o[0], 0, 0, 0);
;     asm volatile("s_waitcnt lgkmcnt(4)" ::: "memory"); SBAR();
;     o[1] = __builtin_amdgcn_mfma_f32_32x32x16_bf16(pa, PK(l1, h1), o[1], 0, 0, 0);
;     asm volatile("s_waitcnt lgkmcnt(2)" ::: "memory"); SBAR();
;     o[2] = __builtin_amdgcn_mfma_f32_32x32x16_bf16(pa, PK(l2, h2), o[2], 0, 0, 0);
;     asm volatile("s_waitcnt lgkmcnt(0)" ::: "memory"); SBAR();
;     o[3] = __builtin_amdgcn_mfma_f32_32x32x16_bf16(pa, PK(l3, h3), o[3], 0, 0, 0);
;     ...
; }
; __device__ __forceinline__ void pv_d0(f32x16* o, int vb, bf16x8 pa0, bf16x8 pa1, bf16x8 pa2, bf16x8 pa3) {
;     __builtin_amdgcn_s_setprio(1);
;     pv_ks<0>(o, vb, pa0); pv_ks<1>(o, vb, pa1); pv_ks<2>(o, vb, pa2); pv_ks<3>(o, vb, pa3);
;     __builtin_amdgcn_s_setprio(0);
; }
; __device__ __forceinline__ void exp_half(f32x16& p) {
; #pragma unroll
;     for (int r = 0; r < 16; ++r) p[r] = __builtin_amdgcn_exp2f(p[r]);
; }
; __device__ __forceinline__ void pack_p(const f32x16& p0, const f32x16& p1, float& l_reg, bf16x8& pa0, bf16x8& pa1, bf16x8& pa2, bf16x8& pa3) {
;     float ps = 0;
; #pragma unroll
;     for (int r = 0; r < 16; ++r) ps += p0[r];
; #pragma unroll
;     for (int r = 0; r < 16; ++r) ps += p1[r];
;     l_reg += ps;
;     ...
;     PK4(p0, 0, pa0); PK4(p0, 8, pa1); PK4(p1, 0, pa2); PK4(p1, 8, pa3);
;     ...
; }
; template <int ND0> __device__ __forceinline__ void qkt(f32x16& p0, f32x16& p1, const char* Ks, const bf16x8* qr, int r32, int hi, int colB0) {
; #pragma unroll
;     for (int d0 = 0; d0 < ND0; ++d0) { const int cb = colB0 + (d0 * 16 + hi * 8) * 2;
;         const bf16x8 b0 = *reinterpret_cast<const bf16x8*>(Ks + KSWZ(r32, cb));
;         const bf16x8 b1 = *reinterpret_cast<const bf16x8*>(Ks + KSWZ(32 + r32, cb));
;         p0 = __builtin_amdgcn_mfma_f32_32x32x16_bf16(b0, qr[d0], p0, 0, 0, 0);
.Lsym_nostage_s2:
	s_waitcnt lgkmcnt(14)
	v_mfma_f32_32x32x16_bf16 v[48:63], v[128:131], v[144:147], v[48:63]
	ds_read_b64_tr_b16 v[144:145], v252 offset:36864
	ds_read_b64_tr_b16 v[146:147], v252 offset:38912
	v_exp_f32_e32 v88, v88
	v_exp_f32_e32 v89, v89
	v_exp_f32_e32 v90, v90
	s_waitcnt lgkmcnt(14)
	v_mfma_f32_32x32x16_bf16 v[32:47], v[128:131], v[148:151], v[32:47]
	ds_read_b64_tr_b16 v[148:149], v252 offset:37376
	ds_read_b64_tr_b16 v[150:151], v252 offset:39424
	v_exp_f32_e32 v91, v91
	v_add_f32_e32 v182, v88, v182
	v_add_f32_e32 v182, v89, v182
	v_cvt_pk_bf16_f32 v132, v88, v89
	v_exp_f32_e32 v92, v92
	s_waitcnt lgkmcnt(11)
	v_mfma_f32_32x32x16_bf16 v[112:127], v[192:195], v[172:175], v[112:127]
	v_exp_f32_e32 v93, v93
	v_add_f32_e32 v182, v90, v182
	v_add_f32_e32 v182, v91, v182
	v_cvt_pk_bf16_f32 v133, v90, v91
	v_mfma_f32_32x32x16_bf16 v[16:31], v[128:131], v[152:155], v[16:31]
	ds_read_b64_tr_b16 v[152:153], v252 offset:37888
	ds_read_b64_tr_b16 v[154:155], v252 offset:39936
	v_exp_f32_e32 v94, v94
	v_exp_f32_e32 v95, v95
	v_add_f32_e32 v182, v92, v182
	v_add_f32_e32 v182, v93, v182
	s_waitcnt lgkmcnt(12)
	v_mfma_f32_32x32x16_bf16 v[96:111], v[196:199], v[172:175], v[96:111]
	v_cvt_pk_bf16_f32 v134, v92, v93
	v_cvt_pk_bf16_f32 v135, v94, v95
	v_add_f32_e32 v182, v94, v182
	v_add_f32_e32 v182, v95, v182
	v_exp_f32_e32 v64, v64
	v_mfma_f32_32x32x16_bf16 v[0:15], v[128:131], v[156:159], v[0:15]
	ds_read_b64_tr_b16 v[156:157], v252 offset:38400
	ds_read_b64_tr_b16 v[158:159], v252 offset:40448
	v_exp_f32_e32 v65, v65
	v_exp_f32_e32 v66, v66
	v_exp_f32_e32 v67, v67
	v_add_f32_e32 v182, v64, v182
	s_waitcnt lgkmcnt(13)
	v_mfma_f32_32x32x16_bf16 v[112:127], v[200:203], v[168:171], v[112:127]
	v_add_f32_e32 v182, v65, v182
	v_cvt_pk_bf16_f32 v136, v64, v65
	v_exp_f32_e32 v68, v68
	v_exp_f32_e32 v69, v69
	s_waitcnt lgkmcnt(6)
	v_mfma_f32_32x32x16_bf16 v[48:63], v[132:135], v[144:147], v[48:63]
	ds_read_b64_tr_b16 v[144:145], v252 offset:40960
	ds_read_b64_tr_b16 v[146:147], v252 offset:43008
	v_add_f32_e32 v182, v66, v182
	v_add_f32_e32 v182, v67, v182
	v_cvt_pk_bf16_f32 v137, v66, v67
	v_exp_f32_e32 v70, v70
	v_mfma_f32_32x32x16_bf16 v[96:111], v[204:207], v[168:171], v[96:111]
	v_exp_f32_e32 v71, v71
	v_add_f32_e32 v182, v68, v182
	v_add_f32_e32 v182, v69, v182
	v_cvt_pk_bf16_f32 v138, v68, v69
	v_cvt_pk_bf16_f32 v139, v70, v71
	v_add_f32_e32 v182, v70, v182
	s_waitcnt lgkmcnt(6)
	v_mfma_f32_32x32x16_bf16 v[32:47], v[132:135], v[148:151], v[32:47]
	ds_read_b64_tr_b16 v[148:149], v252 offset:41472
	ds_read_b64_tr_b16 v[150:151], v252 offset:43520
	v_add_f32_e32 v182, v71, v182
	v_exp_f32_e32 v72, v72
	v_exp_f32_e32 v73, v73
	v_exp_f32_e32 v74, v74
	v_mfma_f32_32x32x16_bf16 v[112:127], v[208:211], v[164:167], v[112:127]
	v_exp_f32_e32 v75, v75
	v_add_f32_e32 v182, v72, v182
	v_add_f32_e32 v182, v73, v182
	v_cvt_pk_bf16_f32 v140, v72, v73
	s_waitcnt lgkmcnt(6)
	v_mfma_f32_32x32x16_bf16 v[16:31], v[132:135], v[152:155], v[16:31]
	ds_read_b64_tr_b16 v[152:153], v252 offset:41984
	ds_read_b64_tr_b16 v[154:155], v252 offset:44032
	v_exp_f32_e32 v76, v76
	v_exp_f32_e32 v77, v77
	v_add_f32_e32 v182, v74, v182
	v_add_f32_e32 v182, v75, v182
	v_mfma_f32_32x32x16_bf16 v[96:111], v[212:215], v[164:167], v[96:111]
	v_cvt_pk_bf16_f32 v141, v74, v75
	v_exp_f32_e32 v78, v78
	v_exp_f32_e32 v79, v79
	v_add_f32_e32 v182, v76, v182
	s_waitcnt lgkmcnt(6)
	v_mfma_f32_32x32x16_bf16 v[0:15], v[132:135], v[156:159], v[0:15]
	ds_read_b64_tr_b16 v[156:157], v252 offset:42496
	ds_read_b64_tr_b16 v[158:159], v252 offset:44544
	v_add_f32_e32 v182, v77, v182
	v_cvt_pk_bf16_f32 v142, v76, v77
	v_cvt_pk_bf16_f32 v143, v78, v79
	v_add_f32_e32 v182, v78, v182
	v_add_f32_e32 v182, v79, v182
	s_cmp_lt_i32 s55, 0
	s_cselect_b32 s100, -1.0, 1.0
	v_mul_f32_e32 v185, s100, v186
	v_mfma_f32_32x32x16_bf16 v[112:127], v[216:219], v[160:163], v[112:127]
	v_fma_f32 v187, -v185, v183, s16
	v_fmamk_f32 v80, v185, 0x00000000, v187
	v_fmamk_f32 v81, v185, 0x3f800000, v187
	v_fmamk_f32 v82, v185, 0x40000000, v187
	v_fmamk_f32 v83, v185, 0x40400000, v187
	v_fmamk_f32 v84, v185, 0x41000000, v187
	v_mfma_f32_32x32x16_bf16 v[96:111], v[220:223], v[160:163], v[96:111]
	v_fmamk_f32 v85, v185, 0x41100000, v187
	v_fmamk_f32 v86, v185, 0x41200000, v187
	v_fmamk_f32 v87, v185, 0x41300000, v187
	v_fmamk_f32 v88, v185, 0x41800000, v187
	v_fmamk_f32 v89, v185, 0x41880000, v187
	v_fmamk_f32 v90, v185, 0x41900000, v187
	s_waitcnt lgkmcnt(6)
	v_mfma_f32_32x32x16_bf16 v[48:63], v[136:139], v[144:147], v[48:63]
	ds_read_b64_tr_b16 v[144:145], v252 offset:45056
	ds_read_b64_tr_b16 v[146:147], v252 offset:47104
	v_fmamk_f32 v91, v185, 0x41980000, v187
	v_fmamk_f32 v92, v185, 0x41c00000, v187
	v_fmamk_f32 v93, v185, 0x41c80000, v187
	v_fmamk_f32 v94, v185, 0x41d00000, v187
	v_fmamk_f32 v95, v185, 0x41d80000, v187
	v_fmamk_f32 v64, v185, 0x42000000, v187
	s_waitcnt lgkmcnt(6)
; #define SBAR() __builtin_amdgcn_sched_barrier(0)
; template <int KS> __device__ __forceinline__ void pv_ks(f32x16* o, int vb, bf16x8 pa) {
;     const s16x4 l0 = tr_read<v_rd_off(0, KS, 0)>(vb), h0 = tr_read<v_rd_off(0, KS, 1)>(vb), l1 = tr_read<v_rd_off(1, KS, 0)>(vb), h1 = tr_read<v_rd_off(1, KS, 1)>(vb);
;     const s16x4 l2 = tr_read<v_rd_off(2, KS, 0)>(vb), h2 = tr_read<v_rd_off(2, KS, 1)>(vb), l3 = tr_read<v_rd_off(3, KS, 0)>(vb), h3 = tr_read<v_rd_off(3, KS, 1)>(vb);
;     ...
;     asm volatile("s_waitcnt lgkmcnt(6)" ::: "memory"); SBAR();
;     o[0] = __builtin_amdgcn_mfma_f32_32x32x16_bf16(pa, PK(l0, h0), o[0], 0, 0, 0);
;     asm volatile("s_waitcnt lgkmcnt(4)" ::: "memory"); SBAR();
;     o[1] = __builtin_amdgcn_mfma_f32_32x32x16_bf16(pa, PK(l1, h1), o[1], 0, 0, 0);
;     asm volatile("s_waitcnt lgkmcnt(2)" ::: "memory"); SBAR();
;     o[2] = __builtin_amdgcn_mfma_f32_32x32x16_bf16(pa, PK(l2, h2), o[2], 0, 0, 0);
;     asm volatile("s_waitcnt lgkmcnt(0)" ::: "memory"); SBAR();
;     o[3] = __builtin_amdgcn_mfma_f32_32x32x16_bf16(pa, PK(l3, h3), o[3], 0, 0, 0);
;     ...
; }
; __device__ __forceinline__ void pv_d0(f32x16* o, int vb, bf16x8 pa0, bf16x8 pa1, bf16x8 pa2, bf16x8 pa3) {
;     __builtin_amdgcn_s_setprio(1);
;     pv_ks<0>(o, vb, pa0); pv_ks<1>(o, vb, pa1); pv_ks<2>(o, vb, pa2); pv_ks<3>(o, vb, pa3);
;     __builtin_amdgcn_s_setprio(0);
; }
; __device__ __forceinline__ void exp_half(f32x16& p) {
; #pragma unroll
;     for (int r = 0; r < 16; ++r) p[r] = __builtin_amdgcn_exp2f(p[r]);
; }
; __device__ __forceinline__ void pack_p(const f32x16& p0, const f32x16& p1, float& l_reg, bf16x8& pa0, bf16x8& pa1, bf16x8& pa2, bf16x8& pa3) {
;     float ps = 0;
; #pragma unroll
;     for (int r = 0; r < 16; ++r) ps += p0[r];
; #pragma unroll
;     for (int r = 0; r < 16; ++r) ps += p1[r];
;     l_reg += ps;
;     ...
;     PK4(p0, 0, pa0); PK4(p0, 8, pa1); PK4(p1, 0, pa2); PK4(p1, 8, pa3);
;     ...
; }
; __device__ __forceinline__ void bias_init(f32x16& p0, f32x16& p1, float base, float nslope2, float nM2, int rel  ) {
;     if (rel <= -63 || rel >= 31) {
;         const float sg = (rel < 0) ? -nslope2 : nslope2, lbv = fmaf(-sg, base, nM2);
; #pragma unroll
;         for (int r = 0; r < 16; ++r) { p0[r] = fmaf((float)((r & 3) + 8 * (r >> 2)), sg, lbv); p1[r] = fmaf((float)((r & 3) + 8 * (r >> 2) + 32), sg, lbv); }
;     } else {
; #pragma unroll
	v_mfma_f32_32x32x16_bf16 v[32:47], v[136:139], v[148:151], v[32:47]
	ds_read_b64_tr_b16 v[148:149], v252 offset:45568
	ds_read_b64_tr_b16 v[150:151], v252 offset:47616
	v_fmamk_f32 v65, v185, 0x42040000, v187
	v_fmamk_f32 v66, v185, 0x42080000, v187
	v_fmamk_f32 v67, v185, 0x420c0000, v187
	v_fmamk_f32 v68, v185, 0x42200000, v187
	v_fmamk_f32 v69, v185, 0x42240000, v187
	v_fmamk_f32 v70, v185, 0x42280000, v187
	s_waitcnt lgkmcnt(6)
	v_mfma_f32_32x32x16_bf16 v[16:31], v[136:139], v[152:155], v[16:31]
	ds_read_b64_tr_b16 v[152:153], v252 offset:46080
	ds_read_b64_tr_b16 v[154:155], v252 offset:48128
	v_fmamk_f32 v71, v185, 0x422c0000, v187
	v_fmamk_f32 v72, v185, 0x42400000, v187
	v_fmamk_f32 v73, v185, 0x42440000, v187
	v_fmamk_f32 v74, v185, 0x42480000, v187
	v_fmamk_f32 v75, v185, 0x424c0000, v187
	v_fmamk_f32 v76, v185, 0x42600000, v187
	s_waitcnt lgkmcnt(6)
	v_mfma_f32_32x32x16_bf16 v[0:15], v[136:139], v[156:159], v[0:15]
	ds_read_b64_tr_b16 v[156:157], v252 offset:46592
	ds_read_b64_tr_b16 v[158:159], v252 offset:48640
	v_fmamk_f32 v77, v185, 0x42640000, v187
	v_fmamk_f32 v78, v185, 0x42680000, v187
	v_fmamk_f32 v79, v185, 0x426c0000, v187
	v_exp_f32_e32 v112, v112
	v_exp_f32_e32 v113, v113
	s_waitcnt lgkmcnt(6)
	v_mfma_f32_32x32x16_bf16 v[48:63], v[140:143], v[144:147], v[48:63]
	ds_read_b64_tr_b16 v[144:145], v252 offset:49152
	ds_read_b64_tr_b16 v[146:147], v252 offset:51200
	v_exp_f32_e32 v114, v114
	v_exp_f32_e32 v115, v115
	v_add_f32_e32 v182, v112, v182
	v_add_f32_e32 v182, v113, v182
	s_waitcnt lgkmcnt(6)
	v_mfma_f32_32x32x16_bf16 v[32:47], v[140:143], v[148:151], v[32:47]
	ds_read_b64_tr_b16 v[148:149], v252 offset:49664
	ds_read_b64_tr_b16 v[150:151], v252 offset:51712
	v_cvt_pk_bf16_f32 v128, v112, v113
	v_exp_f32_e32 v116, v116
	v_exp_f32_e32 v117, v117
	v_add_f32_e32 v182, v114, v182
	s_waitcnt lgkmcnt(6)
	v_mfma_f32_32x32x16_bf16 v[16:31], v[140:143], v[152:155], v[16:31]
	ds_read_b64_tr_b16 v[152:153], v252 offset:50176
	ds_read_b64_tr_b16 v[154:155], v252 offset:52224
	v_add_f32_e32 v182, v115, v182
	v_cvt_pk_bf16_f32 v129, v114, v115
	v_exp_f32_e32 v118, v118
	v_exp_f32_e32 v119, v119
	s_waitcnt lgkmcnt(6)
	v_mfma_f32_32x32x16_bf16 v[0:15], v[140:143], v[156:159], v[0:15]
	ds_read_b64_tr_b16 v[156:157], v252 offset:50688
	ds_read_b64_tr_b16 v[158:159], v252 offset:52736
	v_add_f32_e32 v182, v116, v182
	v_add_f32_e32 v182, v117, v182
	v_cvt_pk_bf16_f32 v130, v116, v117
	v_cvt_pk_bf16_f32 v131, v118, v119
	v_add_f32_e32 v182, v118, v182
	v_add_f32_e32 v182, v119, v182
	s_add_i32 s100, s55, 62
	s_cmp_lt_u32 s100, 93
	s_cbranch_scc0 .Lsym_nodiag_s2
	v_add_f32_e32 v190, 0x00000000, v183
	v_add_f32_e32 v191, 0xc2000000, v183
	v_fma_f32 v80, |v190|, v186, s16
	v_fma_f32 v64, |v191|, v186, s16
	v_add_f32_e32 v190, 0xbf800000, v183
	v_add_f32_e32 v191, 0xc2040000, v183
	v_fma_f32 v81, |v190|, v186, s16
	v_fma_f32 v65, |v191|, v186, s16
	v_add_f32_e32 v190, 0xc0000000, v183
	v_add_f32_e32 v191, 0xc2080000, v183
	v_fma_f32 v82, |v190|, v186, s16
	v_fma_f32 v66, |v191|, v186, s16
	v_add_f32_e32 v190, 0xc0400000, v183
	v_add_f32_e32 v191, 0xc20c0000, v183
	v_fma_f32 v83, |v190|, v186, s16
	v_fma_f32 v67, |v191|, v186, s16
	v_add_f32_e32 v190, 0xc1000000, v183
	v_add_f32_e32 v191, 0xc2200000, v183
	v_fma_f32 v84, |v190|, v186, s16
	v_fma_f32 v68, |v191|, v186, s16
	v_add_f32_e32 v190, 0xc1100000, v183
	v_add_f32_e32 v191, 0xc2240000, v183
	v_fma_f32 v85, |v190|, v186, s16
	v_fma_f32 v69, |v191|, v186, s16
	v_add_f32_e32 v190, 0xc1200000, v183
	v_add_f32_e32 v191, 0xc2280000, v183
	v_fma_f32 v86, |v190|, v186, s16
	v_fma_f32 v70, |v191|, v186, s16
	v_add_f32_e32 v190, 0xc1300000, v183
	v_add_f32_e32 v191, 0xc22c0000, v183
	v_fma_f32 v87, |v190|, v186, s16
	v_fma_f32 v71, |v191|, v186, s16
	v_add_f32_e32 v190, 0xc1800000, v183
	v_add_f32_e32 v191, 0xc2400000, v183
	v_fma_f32 v88, |v190|, v186, s16
	v_fma_f32 v72, |v191|, v186, s16
	v_add_f32_e32 v190, 0xc1880000, v183
	v_add_f32_e32 v191, 0xc2440000, v183
	v_fma_f32 v89, |v190|, v186, s16
	v_fma_f32 v73, |v191|, v186, s16
	v_add_f32_e32 v190, 0xc1900000, v183
	v_add_f32_e32 v191, 0xc2480000, v183
	v_fma_f32 v90, |v190|, v186, s16
	v_fma_f32 v74, |v191|, v186, s16
	v_add_f32_e32 v190, 0xc1980000, v183
	v_add_f32_e32 v191, 0xc24c0000, v183
	v_fma_f32 v91, |v190|, v186, s16
	v_fma_f32 v75, |v191|, v186, s16
	v_add_f32_e32 v190, 0xc1c00000, v183
	v_add_f32_e32 v191, 0xc2600000, v183
	v_fma_f32 v92, |v190|, v186, s16
	v_fma_f32 v76, |v191|, v186, s16
	v_add_f32_e32 v190, 0xc1c80000, v183
	v_add_f32_e32 v191, 0xc2640000, v183
	v_fma_f32 v93, |v190|, v186, s16
	v_fma_f32 v77, |v191|, v186, s16
	v_add_f32_e32 v190, 0xc1d00000, v183
	v_add_f32_e32 v191, 0xc2680000, v183
	v_fma_f32 v94, |v190|, v186, s16
	v_fma_f32 v78, |v191|, v186, s16
	v_add_f32_e32 v190, 0xc1d80000, v183
	v_add_f32_e32 v191, 0xc26c0000, v183
	v_fma_f32 v95, |v190|, v186, s16
	v_fma_f32 v79, |v191|, v186, s16

; template <int KS> __device__ __forceinline__ void pv_ks(f32x16* o, int vb, bf16x8 pa) {
;     const s16x4 l0 = tr_read<v_rd_off(0, KS, 0)>(vb), h0 = tr_read<v_rd_off(0, KS, 1)>(vb), l1 = tr_read<v_rd_off(1, KS, 0)>(vb), h1 = tr_read<v_rd_off(1, KS, 1)>(vb);
;     const s16x4 l2 = tr_read<v_rd_off(2, KS, 0)>(vb), h2 = tr_read<v_rd_off(2, KS, 1)>(vb), l3 = tr_read<v_rd_off(3, KS, 0)>(vb), h3 = tr_read<v_rd_off(3, KS, 1)>(vb);
;     ...
;     asm volatile("s_waitcnt lgkmcnt(6)" ::: "memory"); SBAR();
;     o[0] = __builtin_amdgcn_mfma_f32_32x32x16_bf16(pa, PK(l0, h0), o[0], 0, 0, 0);
;     asm volatile("s_waitcnt lgkmcnt(4)" ::: "memory"); SBAR();
;     o[1] = __builtin_amdgcn_mfma_f32_32x32x16_bf16(pa, PK(l1, h1), o[1], 0, 0, 0);
;     asm volatile("s_waitcnt lgkmcnt(2)" ::: "memory"); SBAR();
;     o[2] = __builtin_amdgcn_mfma_f32_32x32x16_bf16(pa, PK(l2, h2), o[2], 0, 0, 0);
;     asm volatile("s_waitcnt lgkmcnt(0)" ::: "memory"); SBAR();
;     o[3] = __builtin_amdgcn_mfma_f32_32x32x16_bf16(pa, PK(l3, h3), o[3], 0, 0, 0);
;     ...
; }
; __device__ __forceinline__ void pv_d0(f32x16* o, int vb, bf16x8 pa0, bf16x8 pa1, bf16x8 pa2, bf16x8 pa3) {
;     __builtin_amdgcn_s_setprio(1);
;     pv_ks<0>(o, vb, pa0); pv_ks<1>(o, vb, pa1); pv_ks<2>(o, vb, pa2); pv_ks<3>(o, vb, pa3);
;     __builtin_amdgcn_s_setprio(0);
; }
; __device__ __forceinline__ void exp_half(f32x16& p) {
; #pragma unroll
;     for (int r = 0; r < 16; ++r) p[r] = __builtin_amdgcn_exp2f(p[r]);
; }
; __device__ __forceinline__ void pack_p(const f32x16& p0, const f32x16& p1, float& l_reg, bf16x8& pa0, bf16x8& pa1, bf16x8& pa2, bf16x8& pa3) {
;     float ps = 0;
; #pragma unroll
;     for (int r = 0; r < 16; ++r) ps += p0[r];
; #pragma unroll
;     for (int r = 0; r < 16; ++r) ps += p1[r];
;     l_reg += ps;
;     ...
;     PK4(p0, 0, pa0); PK4(p0, 8, pa1); PK4(p1, 0, pa2); PK4(p1, 8, pa3);
;     ...
; }
; template <int ND0> __device__ __forceinline__ void qkt(f32x16& p0, f32x16& p1, const char* Ks, const bf16x8* qr, int r32, int hi, int colB0) {
; #pragma unroll
;     for (int d0 = 0; d0 < ND0; ++d0) { const int cb = colB0 + (d0 * 16 + hi * 8) * 2;
;         const bf16x8 b0 = *reinterpret_cast<const bf16x8*>(Ks + KSWZ(r32, cb));
;         const bf16x8 b1 = *reinterpret_cast<const bf16x8*>(Ks + KSWZ(32 + r32, cb));
;         p0 = __builtin_amdgcn_mfma_f32_32x32x16_bf16(b0, qr[d0], p0, 0, 0, 0);
.Lsym_nostage_s3:
	s_waitcnt lgkmcnt(14)
	v_mfma_f32_32x32x16_bf16 v[48:63], v[128:131], v[144:147], v[48:63]
	ds_read_b64_tr_b16 v[144:145], v252 offset:53248
	ds_read_b64_tr_b16 v[146:147], v252 offset:55296
	v_exp_f32_e32 v120, v120
	v_exp_f32_e32 v121, v121
	v_exp_f32_e32 v122, v122
	s_waitcnt lgkmcnt(14)
	v_mfma_f32_32x32x16_bf16 v[32:47], v[128:131], v[148:151], v[32:47]
	ds_read_b64_tr_b16 v[148:149], v252 offset:53760
	ds_read_b64_tr_b16 v[150:151], v252 offset:55808
	v_exp_f32_e32 v123, v123
	v_add_f32_e32 v182, v120, v182
	v_add_f32_e32 v182, v121, v182
	v_cvt_pk_bf16_f32 v132, v120, v121
	v_exp_f32_e32 v124, v124
	s_waitcnt lgkmcnt(11)
	v_mfma_f32_32x32x16_bf16 v[80:95], v[192:195], v[172:175], v[80:95]
	v_exp_f32_e32 v125, v125
	v_add_f32_e32 v182, v122, v182
	v_add_f32_e32 v182, v123, v182
	v_cvt_pk_bf16_f32 v133, v122, v123
	v_mfma_f32_32x32x16_bf16 v[16:31], v[128:131], v[152:155], v[16:31]
	ds_read_b64_tr_b16 v[152:153], v252 offset:54272
	ds_read_b64_tr_b16 v[154:155], v252 offset:56320
	v_exp_f32_e32 v126, v126
	v_exp_f32_e32 v127, v127
	v_add_f32_e32 v182, v124, v182
	v_add_f32_e32 v182, v125, v182
	s_waitcnt lgkmcnt(12)
	v_mfma_f32_32x32x16_bf16 v[64:79], v[196:199], v[172:175], v[64:79]
	v_cvt_pk_bf16_f32 v134, v124, v125
	v_cvt_pk_bf16_f32 v135, v126, v127
	v_add_f32_e32 v182, v126, v182
	v_add_f32_e32 v182, v127, v182
	v_exp_f32_e32 v96, v96
	v_mfma_f32_32x32x16_bf16 v[0:15], v[128:131], v[156:159], v[0:15]
	ds_read_b64_tr_b16 v[156:157], v252 offset:54784
	ds_read_b64_tr_b16 v[158:159], v252 offset:56832
	v_exp_f32_e32 v97, v97
	v_exp_f32_e32 v98, v98
	v_exp_f32_e32 v99, v99
	v_add_f32_e32 v182, v96, v182
	s_waitcnt lgkmcnt(13)
	v_mfma_f32_32x32x16_bf16 v[80:95], v[200:203], v[168:171], v[80:95]
	v_add_f32_e32 v182, v97, v182
	v_cvt_pk_bf16_f32 v136, v96, v97
	v_exp_f32_e32 v100, v100
	v_exp_f32_e32 v101, v101
	s_waitcnt lgkmcnt(6)
	v_mfma_f32_32x32x16_bf16 v[48:63], v[132:135], v[144:147], v[48:63]
	ds_read_b64_tr_b16 v[144:145], v252 offset:57344
	ds_read_b64_tr_b16 v[146:147], v252 offset:59392
	v_add_f32_e32 v182, v98, v182
	v_add_f32_e32 v182, v99, v182
	v_cvt_pk_bf16_f32 v137, v98, v99
	v_exp_f32_e32 v102, v102
	v_mfma_f32_32x32x16_bf16 v[64:79], v[204:207], v[168:171], v[64:79]
	v_exp_f32_e32 v103, v103
	v_add_f32_e32 v182, v100, v182
	v_add_f32_e32 v182, v101, v182
	v_cvt_pk_bf16_f32 v138, v100, v101
	v_cvt_pk_bf16_f32 v139, v102, v103
	v_add_f32_e32 v182, v102, v182
	s_waitcnt lgkmcnt(6)
	v_mfma_f32_32x32x16_bf16 v[32:47], v[132:135], v[148:151], v[32:47]
	ds_read_b64_tr_b16 v[148:149], v252 offset:57856
	ds_read_b64_tr_b16 v[150:151], v252 offset:59904
	v_add_f32_e32 v182, v103, v182
	v_exp_f32_e32 v104, v104
	v_exp_f32_e32 v105, v105
	v_exp_f32_e32 v106, v106
	v_mfma_f32_32x32x16_bf16 v[80:95], v[208:211], v[164:167], v[80:95]
	v_exp_f32_e32 v107, v107
	v_add_f32_e32 v182, v104, v182
	v_add_f32_e32 v182, v105, v182
	v_cvt_pk_bf16_f32 v140, v104, v105
	s_waitcnt lgkmcnt(6)
	v_mfma_f32_32x32x16_bf16 v[16:31], v[132:135], v[152:155], v[16:31]
	ds_read_b64_tr_b16 v[152:153], v252 offset:58368
	ds_read_b64_tr_b16 v[154:155], v252 offset:60416
	v_exp_f32_e32 v108, v108
	v_exp_f32_e32 v109, v109
	v_add_f32_e32 v182, v106, v182
	v_add_f32_e32 v182, v107, v182
	v_mfma_f32_32x32x16_bf16 v[64:79], v[212:215], v[164:167], v[64:79]
	v_cvt_pk_bf16_f32 v141, v106, v107
	v_exp_f32_e32 v110, v110
	v_exp_f32_e32 v111, v111
	v_add_f32_e32 v182, v108, v182
	s_waitcnt lgkmcnt(6)
	v_mfma_f32_32x32x16_bf16 v[0:15], v[132:135], v[156:159], v[0:15]
	ds_read_b64_tr_b16 v[156:157], v252 offset:58880
	ds_read_b64_tr_b16 v[158:159], v252 offset:60928
	v_add_f32_e32 v182, v109, v182
	v_cvt_pk_bf16_f32 v142, v108, v109
	v_cvt_pk_bf16_f32 v143, v110, v111
	v_add_f32_e32 v182, v110, v182
	v_add_f32_e32 v182, v111, v182
	s_cmp_lt_i32 s55, 0
	s_cselect_b32 s100, -1.0, 1.0
	v_mul_f32_e32 v185, s100, v186
	v_mfma_f32_32x32x16_bf16 v[80:95], v[216:219], v[160:163], v[80:95]
	v_fma_f32 v187, -v185, v183, s16
	v_fmamk_f32 v112, v185, 0x00000000, v187
	v_fmamk_f32 v113, v185, 0x3f800000, v187
	v_fmamk_f32 v114, v185, 0x40000000, v187
	v_fmamk_f32 v115, v185, 0x40400000, v187
	v_fmamk_f32 v116, v185, 0x41000000, v187
	v_mfma_f32_32x32x16_bf16 v[64:79], v[220:223], v[160:163], v[64:79]
	v_fmamk_f32 v117, v185, 0x41100000, v187
	v_fmamk_f32 v118, v185, 0x41200000, v187
	v_fmamk_f32 v119, v185, 0x41300000, v187
	v_fmamk_f32 v120, v185, 0x41800000, v187
	v_fmamk_f32 v121, v185, 0x41880000, v187
	v_fmamk_f32 v122, v185, 0x41900000, v187
	s_waitcnt lgkmcnt(6)
	v_mfma_f32_32x32x16_bf16 v[48:63], v[136:139], v[144:147], v[48:63]
	ds_read_b64_tr_b16 v[144:145], v252 offset:61440
	ds_read_b64_tr_b16 v[146:147], v252 offset:63488
	v_fmamk_f32 v123, v185, 0x41980000, v187
	v_fmamk_f32 v124, v185, 0x41c00000, v187
	v_fmamk_f32 v125, v185, 0x41c80000, v187
	v_fmamk_f32 v126, v185, 0x41d00000, v187
	v_fmamk_f32 v127, v185, 0x41d80000, v187
	v_fmamk_f32 v96, v185, 0x42000000, v187
	s_waitcnt lgkmcnt(6)
; #define SBAR() __builtin_amdgcn_sched_barrier(0)
; template <int KS> __device__ __forceinline__ void pv_ks(f32x16* o, int vb, bf16x8 pa) {
;     const s16x4 l0 = tr_read<v_rd_off(0, KS, 0)>(vb), h0 = tr_read<v_rd_off(0, KS, 1)>(vb), l1 = tr_read<v_rd_off(1, KS, 0)>(vb), h1 = tr_read<v_rd_off(1, KS, 1)>(vb);
;     const s16x4 l2 = tr_read<v_rd_off(2, KS, 0)>(vb), h2 = tr_read<v_rd_off(2, KS, 1)>(vb), l3 = tr_read<v_rd_off(3, KS, 0)>(vb), h3 = tr_read<v_rd_off(3, KS, 1)>(vb);
;     ...
;     asm volatile("s_waitcnt lgkmcnt(6)" ::: "memory"); SBAR();
;     o[0] = __builtin_amdgcn_mfma_f32_32x32x16_bf16(pa, PK(l0, h0), o[0], 0, 0, 0);
;     asm volatile("s_waitcnt lgkmcnt(4)" ::: "memory"); SBAR();
;     o[1] = __builtin_amdgcn_mfma_f32_32x32x16_bf16(pa, PK(l1, h1), o[1], 0, 0, 0);
;     asm volatile("s_waitcnt lgkmcnt(2)" ::: "memory"); SBAR();
;     o[2] = __builtin_amdgcn_mfma_f32_32x32x16_bf16(pa, PK(l2, h2), o[2], 0, 0, 0);
;     asm volatile("s_waitcnt lgkmcnt(0)" ::: "memory"); SBAR();
;     o[3] = __builtin_amdgcn_mfma_f32_32x32x16_bf16(pa, PK(l3, h3), o[3], 0, 0, 0);
;     ...
; }
; __device__ __forceinline__ void pv_d0(f32x16* o, int vb, bf16x8 pa0, bf16x8 pa1, bf16x8 pa2, bf16x8 pa3) {
;     __builtin_amdgcn_s_setprio(1);
;     pv_ks<0>(o, vb, pa0); pv_ks<1>(o, vb, pa1); pv_ks<2>(o, vb, pa2); pv_ks<3>(o, vb, pa3);
;     __builtin_amdgcn_s_setprio(0);
; }
; __device__ __forceinline__ void exp_half(f32x16& p) {
; #pragma unroll
;     for (int r = 0; r < 16; ++r) p[r] = __builtin_amdgcn_exp2f(p[r]);
; }
; __device__ __forceinline__ void pack_p(const f32x16& p0, const f32x16& p1, float& l_reg, bf16x8& pa0, bf16x8& pa1, bf16x8& pa2, bf16x8& pa3) {
;     float ps = 0;
; #pragma unroll
;     for (int r = 0; r < 16; ++r) ps += p0[r];
; #pragma unroll
;     for (int r = 0; r < 16; ++r) ps += p1[r];
;     l_reg += ps;
;     ...
;     PK4(p0, 0, pa0); PK4(p0, 8, pa1); PK4(p1, 0, pa2); PK4(p1, 8, pa3);
;     ...
; }
; __device__ __forceinline__ void bias_init(f32x16& p0, f32x16& p1, float base, float nslope2, float nM2, int rel  ) {
;     if (rel <= -63 || rel >= 31) {
;         const float sg = (rel < 0) ? -nslope2 : nslope2, lbv = fmaf(-sg, base, nM2);
; #pragma unroll
;         for (int r = 0; r < 16; ++r) { p0[r] = fmaf((float)((r & 3) + 8 * (r >> 2)), sg, lbv); p1[r] = fmaf((float)((r & 3) + 8 * (r >> 2) + 32), sg, lbv); }
;     } else {
; #pragma unroll
	v_mfma_f32_32x32x16_bf16 v[32:47], v[136:139], v[148:151], v[32:47]
	ds_read_b64_tr_b16 v[148:149], v252 offset:61952
	ds_read_b64_tr_b16 v[150:151], v252 offset:64000
	v_fmamk_f32 v97, v185, 0x42040000, v187
	v_fmamk_f32 v98, v185, 0x42080000, v187
	v_fmamk_f32 v99, v185, 0x420c0000, v187
	v_fmamk_f32 v100, v185, 0x42200000, v187
	v_fmamk_f32 v101, v185, 0x42240000, v187
	v_fmamk_f32 v102, v185, 0x42280000, v187
	s_waitcnt lgkmcnt(6)
	v_mfma_f32_32x32x16_bf16 v[16:31], v[136:139], v[152:155], v[16:31]
	ds_read_b64_tr_b16 v[152:153], v252 offset:62464
	ds_read_b64_tr_b16 v[154:155], v252 offset:64512
	v_fmamk_f32 v103, v185, 0x422c0000, v187
	v_fmamk_f32 v104, v185, 0x42400000, v187
	v_fmamk_f32 v105, v185, 0x42440000, v187
	v_fmamk_f32 v106, v185, 0x42480000, v187
	v_fmamk_f32 v107, v185, 0x424c0000, v187
	v_fmamk_f32 v108, v185, 0x42600000, v187
	s_waitcnt lgkmcnt(6)
	v_mfma_f32_32x32x16_bf16 v[0:15], v[136:139], v[156:159], v[0:15]
	ds_read_b64_tr_b16 v[156:157], v252 offset:62976
	ds_read_b64_tr_b16 v[158:159], v252 offset:65024
	v_fmamk_f32 v109, v185, 0x42640000, v187
	v_fmamk_f32 v110, v185, 0x42680000, v187
	v_fmamk_f32 v111, v185, 0x426c0000, v187
	v_exp_f32_e32 v80, v80
	v_exp_f32_e32 v81, v81
	s_waitcnt lgkmcnt(6)
	v_mfma_f32_32x32x16_bf16 v[48:63], v[140:143], v[144:147], v[48:63]
	ds_read_b64_tr_b16 v[144:145], v252 offset:0
	ds_read_b64_tr_b16 v[146:147], v252 offset:2048
	v_exp_f32_e32 v82, v82
	v_exp_f32_e32 v83, v83
	v_add_f32_e32 v182, v80, v182
	v_add_f32_e32 v182, v81, v182
	s_waitcnt lgkmcnt(6)
	v_mfma_f32_32x32x16_bf16 v[32:47], v[140:143], v[148:151], v[32:47]
	ds_read_b64_tr_b16 v[148:149], v252 offset:512
	ds_read_b64_tr_b16 v[150:151], v252 offset:2560
	v_cvt_pk_bf16_f32 v128, v80, v81
	v_exp_f32_e32 v84, v84
	v_exp_f32_e32 v85, v85
	v_add_f32_e32 v182, v82, v182
	s_waitcnt lgkmcnt(6)
	v_mfma_f32_32x32x16_bf16 v[16:31], v[140:143], v[152:155], v[16:31]
	ds_read_b64_tr_b16 v[152:153], v252 offset:1024
	ds_read_b64_tr_b16 v[154:155], v252 offset:3072
	v_add_f32_e32 v182, v83, v182
	v_cvt_pk_bf16_f32 v129, v82, v83
	v_exp_f32_e32 v86, v86
	v_exp_f32_e32 v87, v87
	s_waitcnt lgkmcnt(6)
	v_mfma_f32_32x32x16_bf16 v[0:15], v[140:143], v[156:159], v[0:15]
	ds_read_b64_tr_b16 v[156:157], v252 offset:1536
	ds_read_b64_tr_b16 v[158:159], v252 offset:3584
	v_add_f32_e32 v182, v84, v182
	v_add_f32_e32 v182, v85, v182
	v_cvt_pk_bf16_f32 v130, v84, v85
	v_cvt_pk_bf16_f32 v131, v86, v87
	v_add_f32_e32 v182, v86, v182
	v_add_f32_e32 v182, v87, v182
	s_add_i32 s100, s55, 62
	s_cmp_lt_u32 s100, 93
	s_cbranch_scc0 .Lsym_nodiag_s3
	v_add_f32_e32 v190, 0x00000000, v183
	v_add_f32_e32 v191, 0xc2000000, v183
	v_fma_f32 v112, |v190|, v186, s16
	v_fma_f32 v96, |v191|, v186, s16
	v_add_f32_e32 v190, 0xbf800000, v183
	v_add_f32_e32 v191, 0xc2040000, v183
	v_fma_f32 v113, |v190|, v186, s16
	v_fma_f32 v97, |v191|, v186, s16
	v_add_f32_e32 v190, 0xc0000000, v183
	v_add_f32_e32 v191, 0xc2080000, v183
	v_fma_f32 v114, |v190|, v186, s16
	v_fma_f32 v98, |v191|, v186, s16
	v_add_f32_e32 v190, 0xc0400000, v183
	v_add_f32_e32 v191, 0xc20c0000, v183
	v_fma_f32 v115, |v190|, v186, s16
	v_fma_f32 v99, |v191|, v186, s16
	v_add_f32_e32 v190, 0xc1000000, v183
	v_add_f32_e32 v191, 0xc2200000, v183
	v_fma_f32 v116, |v190|, v186, s16
	v_fma_f32 v100, |v191|, v186, s16
	v_add_f32_e32 v190, 0xc1100000, v183
	v_add_f32_e32 v191, 0xc2240000, v183
	v_fma_f32 v117, |v190|, v186, s16
	v_fma_f32 v101, |v191|, v186, s16
	v_add_f32_e32 v190, 0xc1200000, v183
	v_add_f32_e32 v191, 0xc2280000, v183
	v_fma_f32 v118, |v190|, v186, s16
	v_fma_f32 v102, |v191|, v186, s16
	v_add_f32_e32 v190, 0xc1300000, v183
	v_add_f32_e32 v191, 0xc22c0000, v183
	v_fma_f32 v119, |v190|, v186, s16
	v_fma_f32 v103, |v191|, v186, s16
	v_add_f32_e32 v190, 0xc1800000, v183
	v_add_f32_e32 v191, 0xc2400000, v183
	v_fma_f32 v120, |v190|, v186, s16
	v_fma_f32 v104, |v191|, v186, s16
	v_add_f32_e32 v190, 0xc1880000, v183
	v_add_f32_e32 v191, 0xc2440000, v183
	v_fma_f32 v121, |v190|, v186, s16
	v_fma_f32 v105, |v191|, v186, s16
	v_add_f32_e32 v190, 0xc1900000, v183
	v_add_f32_e32 v191, 0xc2480000, v183
	v_fma_f32 v122, |v190|, v186, s16
	v_fma_f32 v106, |v191|, v186, s16
	v_add_f32_e32 v190, 0xc1980000, v183
	v_add_f32_e32 v191, 0xc24c0000, v183
	v_fma_f32 v123, |v190|, v186, s16
	v_fma_f32 v107, |v191|, v186, s16
	v_add_f32_e32 v190, 0xc1c00000, v183
	v_add_f32_e32 v191, 0xc2600000, v183
	v_fma_f32 v124, |v190|, v186, s16
	v_fma_f32 v108, |v191|, v186, s16
	v_add_f32_e32 v190, 0xc1c80000, v183
	v_add_f32_e32 v191, 0xc2640000, v183
	v_fma_f32 v125, |v190|, v186, s16
	v_fma_f32 v109, |v191|, v186, s16
	v_add_f32_e32 v190, 0xc1d00000, v183
	v_add_f32_e32 v191, 0xc2680000, v183
	v_fma_f32 v126, |v190|, v186, s16
	v_fma_f32 v110, |v191|, v186, s16
	v_add_f32_e32 v190, 0xc1d80000, v183
	v_add_f32_e32 v191, 0xc26c0000, v183
	v_fma_f32 v127, |v190|, v186, s16
	v_fma_f32 v111, |v191|, v186, s16
